# fix phase SGU LayerNorm pass 1: the 16 row-chunk loads of a thread issued before the first wait (loop of 4 load-wait trips unrolled, arithmetic order unchanged)
# baseline (speedup 1.0000x reference)
; __device__ __forceinline__ float bflo(unsigned w) { return __uint_as_float(w << 16); }
; __device__ __forceinline__ float bfhi(unsigned w) { return __uint_as_float(w & 0xffff0000u); }
; __device__ __forceinline__ void phase_fix(KP kp, int l, unsigned char* shm) {
;     ...
;         const bf16_t* src = VG + (size_t)(rbase + row) * 512 + qtr * 128;
;         float s = 0.f, ss = 0.f;
; #pragma unroll 4
;         for (int e = 0; e < 16; ++e) {
;           const u32x4 rw = *(const u32x4*)(src + e * 8);
; #pragma unroll
;           for (int q = 0; q < 4; ++q) { const float a = bflo(rw[q]), b = bfhi(rw[q]); s += a + b; ss += a * a + b * b; }
;         }
.LBB0_2812:
	v_lshl_add_u64 v[92:93], v[4:5], 0, s[28:29]
	s_mov_b64 s[10:11], 0x100
	global_load_dwordx4 v[6:9], v[92:93], off offset:16
	global_load_dwordx4 v[10:13], v[92:93], off offset:32
	global_load_dwordx4 v[18:21], v[92:93], off
	global_load_dwordx4 v[22:25], v[92:93], off offset:48
	global_load_dwordx4 v[96:99], v[92:93], off offset:80
	global_load_dwordx4 v[100:103], v[92:93], off offset:96
	global_load_dwordx4 v[104:107], v[92:93], off offset:64
	global_load_dwordx4 v[108:111], v[92:93], off offset:112
	global_load_dwordx4 v[112:115], v[92:93], off offset:144
	global_load_dwordx4 v[116:119], v[92:93], off offset:160
	global_load_dwordx4 v[120:123], v[92:93], off offset:128
	global_load_dwordx4 v[124:127], v[92:93], off offset:176
	global_load_dwordx4 v[128:131], v[92:93], off offset:208
	global_load_dwordx4 v[132:135], v[92:93], off offset:224
	global_load_dwordx4 v[136:139], v[92:93], off offset:192
	global_load_dwordx4 v[140:143], v[92:93], off offset:240
	s_waitcnt vmcnt(15)
	v_lshlrev_b32_e32 v15, 16, v6
	v_and_b32_e32 v27, 0xffff0000, v6
	v_lshlrev_b32_e32 v31, 16, v8
	v_and_b32_e32 v33, 0xffff0000, v8
	s_waitcnt vmcnt(13)
	v_lshlrev_b32_e32 v69, 16, v18
	v_and_b32_e32 v71, 0xffff0000, v18
	v_lshlrev_b32_e32 v73, 16, v19
	v_and_b32_e32 v19, 0xffff0000, v19
	v_mul_f32_e32 v14, v15, v15
	v_mul_f32_e32 v26, v27, v27
	v_mul_f32_e32 v30, v31, v31
	v_mul_f32_e32 v32, v33, v33
	v_mul_f32_e32 v68, v69, v69
	v_mul_f32_e32 v70, v71, v71
	v_lshlrev_b32_e32 v35, 16, v9
	v_and_b32_e32 v9, 0xffff0000, v9
	v_lshlrev_b32_e32 v75, 16, v20
	v_and_b32_e32 v77, 0xffff0000, v20
	v_mul_f32_e32 v72, v73, v73
	v_mul_f32_e32 v18, v19, v19
	v_pk_add_f32 v[14:15], v[14:15], v[26:27]
	v_pk_add_f32 v[26:27], v[30:31], v[32:33]
	v_pk_add_f32 v[32:33], v[68:69], v[70:71]
	v_lshlrev_b32_e32 v79, 16, v21
	v_and_b32_e32 v21, 0xffff0000, v21
	v_mul_f32_e32 v34, v35, v35
	v_mul_f32_e32 v8, v9, v9
	v_mul_f32_e32 v74, v75, v75
	v_mul_f32_e32 v76, v77, v77
	v_pk_add_f32 v[18:19], v[72:73], v[18:19]
	v_pk_add_f32 v[2:3], v[2:3], v[32:33]
	v_mul_f32_e32 v78, v79, v79
	v_mul_f32_e32 v20, v21, v21
	v_pk_add_f32 v[8:9], v[34:35], v[8:9]
	v_pk_add_f32 v[34:35], v[74:75], v[76:77]
	v_pk_add_f32 v[2:3], v[18:19], v[2:3]
	v_lshlrev_b32_e32 v29, 16, v7
	v_and_b32_e32 v7, 0xffff0000, v7
	v_pk_add_f32 v[20:21], v[78:79], v[20:21]
	v_pk_add_f32 v[2:3], v[34:35], v[2:3]
	v_mul_f32_e32 v28, v29, v29
	v_mul_f32_e32 v6, v7, v7
	v_pk_add_f32 v[2:3], v[20:21], v[2:3]
	v_pk_add_f32 v[6:7], v[28:29], v[6:7]
	v_pk_add_f32 v[2:3], v[2:3], v[14:15]
	v_lshlrev_b32_e32 v57, 16, v10
	v_and_b32_e32 v59, 0xffff0000, v10
	v_pk_add_f32 v[2:3], v[6:7], v[2:3]
	v_lshlrev_b32_e32 v61, 16, v11
	v_and_b32_e32 v11, 0xffff0000, v11
	v_mul_f32_e32 v56, v57, v57
	v_mul_f32_e32 v58, v59, v59
	v_pk_add_f32 v[2:3], v[26:27], v[2:3]
	v_lshlrev_b32_e32 v63, 16, v12
	v_and_b32_e32 v65, 0xffff0000, v12
	v_mul_f32_e32 v60, v61, v61
	v_mul_f32_e32 v10, v11, v11
	v_pk_add_f32 v[28:29], v[56:57], v[58:59]
	v_pk_add_f32 v[2:3], v[8:9], v[2:3]
	v_lshlrev_b32_e32 v67, 16, v13
	v_and_b32_e32 v13, 0xffff0000, v13
	v_mul_f32_e32 v62, v63, v63
	v_mul_f32_e32 v64, v65, v65
	v_pk_add_f32 v[10:11], v[60:61], v[10:11]
	v_pk_add_f32 v[2:3], v[2:3], v[28:29]
	v_mul_f32_e32 v66, v67, v67
	v_mul_f32_e32 v12, v13, v13
	s_waitcnt vmcnt(12)
	v_lshlrev_b32_e32 v81, 16, v22
	v_and_b32_e32 v83, 0xffff0000, v22
	v_pk_add_f32 v[30:31], v[62:63], v[64:65]
	v_pk_add_f32 v[2:3], v[10:11], v[2:3]
	v_lshlrev_b32_e32 v85, 16, v23
	v_and_b32_e32 v23, 0xffff0000, v23
	v_pk_add_f32 v[12:13], v[66:67], v[12:13]
	v_mul_f32_e32 v80, v81, v81
	v_mul_f32_e32 v82, v83, v83
	v_pk_add_f32 v[2:3], v[30:31], v[2:3]
	v_lshlrev_b32_e32 v87, 16, v24
	v_and_b32_e32 v89, 0xffff0000, v24
	v_mul_f32_e32 v84, v85, v85
	v_mul_f32_e32 v22, v23, v23
	v_pk_add_f32 v[56:57], v[80:81], v[82:83]
	v_pk_add_f32 v[2:3], v[12:13], v[2:3]
	v_lshlrev_b32_e32 v91, 16, v25
	v_and_b32_e32 v25, 0xffff0000, v25
	v_mul_f32_e32 v86, v87, v87
	v_mul_f32_e32 v88, v89, v89
	v_pk_add_f32 v[22:23], v[84:85], v[22:23]
	v_pk_add_f32 v[2:3], v[2:3], v[56:57]
	v_mul_f32_e32 v90, v91, v91
	v_mul_f32_e32 v24, v25, v25
	v_pk_add_f32 v[58:59], v[86:87], v[88:89]
	v_pk_add_f32 v[2:3], v[22:23], v[2:3]
	v_pk_add_f32 v[24:25], v[90:91], v[24:25]
	v_pk_add_f32 v[2:3], v[58:59], v[2:3]
	s_nop 0
	v_pk_add_f32 v[2:3], v[24:25], v[2:3]
	s_waitcnt vmcnt(11)
	v_lshlrev_b32_e32 v15, 16, v96
	v_and_b32_e32 v27, 0xffff0000, v96
	v_lshlrev_b32_e32 v31, 16, v98
	v_and_b32_e32 v33, 0xffff0000, v98
	s_waitcnt vmcnt(9)
; __device__ __forceinline__ float bflo(unsigned w) { return __uint_as_float(w << 16); }
; __device__ __forceinline__ float bfhi(unsigned w) { return __uint_as_float(w & 0xffff0000u); }
; __device__ __forceinline__ void phase_fix(KP kp, int l, unsigned char* shm) {
;     ...
;         const bf16_t* src = VG + (size_t)(rbase + row) * 512 + qtr * 128;
;         float s = 0.f, ss = 0.f;
; #pragma unroll 4
;         for (int e = 0; e < 16; ++e) {
;           const u32x4 rw = *(const u32x4*)(src + e * 8);
; #pragma unroll
;           for (int q = 0; q < 4; ++q) { const float a = bflo(rw[q]), b = bfhi(rw[q]); s += a + b; ss += a * a + b * b; }
;         }
	v_lshlrev_b32_e32 v69, 16, v104
	v_and_b32_e32 v71, 0xffff0000, v104
	v_lshlrev_b32_e32 v73, 16, v105
	v_and_b32_e32 v105, 0xffff0000, v105
	v_mul_f32_e32 v14, v15, v15
	v_mul_f32_e32 v26, v27, v27
	v_mul_f32_e32 v30, v31, v31
	v_mul_f32_e32 v32, v33, v33
	v_mul_f32_e32 v68, v69, v69
	v_mul_f32_e32 v70, v71, v71
	v_lshlrev_b32_e32 v35, 16, v99
	v_and_b32_e32 v99, 0xffff0000, v99
	v_lshlrev_b32_e32 v75, 16, v106
	v_and_b32_e32 v77, 0xffff0000, v106
	v_mul_f32_e32 v72, v73, v73
	v_mul_f32_e32 v104, v105, v105
	v_pk_add_f32 v[14:15], v[14:15], v[26:27]
	v_pk_add_f32 v[26:27], v[30:31], v[32:33]
	v_pk_add_f32 v[32:33], v[68:69], v[70:71]
	v_lshlrev_b32_e32 v79, 16, v107
	v_and_b32_e32 v107, 0xffff0000, v107
	v_mul_f32_e32 v34, v35, v35
	v_mul_f32_e32 v98, v99, v99
	v_mul_f32_e32 v74, v75, v75
	v_mul_f32_e32 v76, v77, v77
	v_pk_add_f32 v[104:105], v[72:73], v[104:105]
	v_pk_add_f32 v[2:3], v[2:3], v[32:33]
	v_mul_f32_e32 v78, v79, v79
	v_mul_f32_e32 v106, v107, v107
	v_pk_add_f32 v[98:99], v[34:35], v[98:99]
	v_pk_add_f32 v[34:35], v[74:75], v[76:77]
	v_pk_add_f32 v[2:3], v[104:105], v[2:3]
	v_lshlrev_b32_e32 v29, 16, v97
	v_and_b32_e32 v97, 0xffff0000, v97
	v_pk_add_f32 v[106:107], v[78:79], v[106:107]
	v_pk_add_f32 v[2:3], v[34:35], v[2:3]
	v_mul_f32_e32 v28, v29, v29
	v_mul_f32_e32 v96, v97, v97
	v_pk_add_f32 v[2:3], v[106:107], v[2:3]
	v_pk_add_f32 v[96:97], v[28:29], v[96:97]
	v_pk_add_f32 v[2:3], v[2:3], v[14:15]
	v_lshlrev_b32_e32 v57, 16, v100
	v_and_b32_e32 v59, 0xffff0000, v100
	v_pk_add_f32 v[2:3], v[96:97], v[2:3]
	v_lshlrev_b32_e32 v61, 16, v101
	v_and_b32_e32 v101, 0xffff0000, v101
	v_mul_f32_e32 v56, v57, v57
	v_mul_f32_e32 v58, v59, v59
	v_pk_add_f32 v[2:3], v[26:27], v[2:3]
	v_lshlrev_b32_e32 v63, 16, v102
	v_and_b32_e32 v65, 0xffff0000, v102
	v_mul_f32_e32 v60, v61, v61
	v_mul_f32_e32 v100, v101, v101
	v_pk_add_f32 v[28:29], v[56:57], v[58:59]
	v_pk_add_f32 v[2:3], v[98:99], v[2:3]
	v_lshlrev_b32_e32 v67, 16, v103
	v_and_b32_e32 v103, 0xffff0000, v103
	v_mul_f32_e32 v62, v63, v63
	v_mul_f32_e32 v64, v65, v65
	v_pk_add_f32 v[100:101], v[60:61], v[100:101]
	v_pk_add_f32 v[2:3], v[2:3], v[28:29]
	v_mul_f32_e32 v66, v67, v67
	v_mul_f32_e32 v102, v103, v103
	s_waitcnt vmcnt(8)
	v_lshlrev_b32_e32 v81, 16, v108
	v_and_b32_e32 v83, 0xffff0000, v108
	v_pk_add_f32 v[30:31], v[62:63], v[64:65]
	v_pk_add_f32 v[2:3], v[100:101], v[2:3]
	v_lshlrev_b32_e32 v85, 16, v109
	v_and_b32_e32 v109, 0xffff0000, v109
	v_pk_add_f32 v[102:103], v[66:67], v[102:103]
	v_mul_f32_e32 v80, v81, v81
	v_mul_f32_e32 v82, v83, v83
	v_pk_add_f32 v[2:3], v[30:31], v[2:3]
	v_lshlrev_b32_e32 v87, 16, v110
	v_and_b32_e32 v89, 0xffff0000, v110
	v_mul_f32_e32 v84, v85, v85
	v_mul_f32_e32 v108, v109, v109
	v_pk_add_f32 v[56:57], v[80:81], v[82:83]
	v_pk_add_f32 v[2:3], v[102:103], v[2:3]
	v_lshlrev_b32_e32 v91, 16, v111
	v_and_b32_e32 v111, 0xffff0000, v111
	v_mul_f32_e32 v86, v87, v87
	v_mul_f32_e32 v88, v89, v89
	v_pk_add_f32 v[108:109], v[84:85], v[108:109]
	v_pk_add_f32 v[2:3], v[2:3], v[56:57]
	v_mul_f32_e32 v90, v91, v91
	v_mul_f32_e32 v110, v111, v111
	v_pk_add_f32 v[58:59], v[86:87], v[88:89]
	v_pk_add_f32 v[2:3], v[108:109], v[2:3]
	v_pk_add_f32 v[110:111], v[90:91], v[110:111]
	v_pk_add_f32 v[2:3], v[58:59], v[2:3]
	s_nop 0
	v_pk_add_f32 v[2:3], v[110:111], v[2:3]
	s_waitcnt vmcnt(7)
	v_lshlrev_b32_e32 v15, 16, v112
	v_and_b32_e32 v27, 0xffff0000, v112
	v_lshlrev_b32_e32 v31, 16, v114
	v_and_b32_e32 v33, 0xffff0000, v114
	s_waitcnt vmcnt(5)
	v_lshlrev_b32_e32 v69, 16, v120
	v_and_b32_e32 v71, 0xffff0000, v120
	v_lshlrev_b32_e32 v73, 16, v121
	v_and_b32_e32 v121, 0xffff0000, v121
	v_mul_f32_e32 v14, v15, v15
	v_mul_f32_e32 v26, v27, v27
	v_mul_f32_e32 v30, v31, v31
	v_mul_f32_e32 v32, v33, v33
	v_mul_f32_e32 v68, v69, v69
	v_mul_f32_e32 v70, v71, v71
	v_lshlrev_b32_e32 v35, 16, v115
	v_and_b32_e32 v115, 0xffff0000, v115
	v_lshlrev_b32_e32 v75, 16, v122
	v_and_b32_e32 v77, 0xffff0000, v122
	v_mul_f32_e32 v72, v73, v73
	v_mul_f32_e32 v120, v121, v121
	v_pk_add_f32 v[14:15], v[14:15], v[26:27]
	v_pk_add_f32 v[26:27], v[30:31], v[32:33]
	v_pk_add_f32 v[32:33], v[68:69], v[70:71]
	v_lshlrev_b32_e32 v79, 16, v123
	v_and_b32_e32 v123, 0xffff0000, v123
	v_mul_f32_e32 v34, v35, v35
	v_mul_f32_e32 v114, v115, v115
	v_mul_f32_e32 v74, v75, v75
	v_mul_f32_e32 v76, v77, v77
	v_pk_add_f32 v[120:121], v[72:73], v[120:121]
	v_pk_add_f32 v[2:3], v[2:3], v[32:33]
	v_mul_f32_e32 v78, v79, v79
	v_mul_f32_e32 v122, v123, v123
	v_pk_add_f32 v[114:115], v[34:35], v[114:115]
	v_pk_add_f32 v[34:35], v[74:75], v[76:77]
	v_pk_add_f32 v[2:3], v[120:121], v[2:3]
	v_lshlrev_b32_e32 v29, 16, v113
	v_and_b32_e32 v113, 0xffff0000, v113
	v_pk_add_f32 v[122:123], v[78:79], v[122:123]
	v_pk_add_f32 v[2:3], v[34:35], v[2:3]
	v_mul_f32_e32 v28, v29, v29
	v_mul_f32_e32 v112, v113, v113
	v_pk_add_f32 v[2:3], v[122:123], v[2:3]
	v_pk_add_f32 v[112:113], v[28:29], v[112:113]
	v_pk_add_f32 v[2:3], v[2:3], v[14:15]
	v_lshlrev_b32_e32 v57, 16, v116
	v_and_b32_e32 v59, 0xffff0000, v116
	v_pk_add_f32 v[2:3], v[112:113], v[2:3]
	v_lshlrev_b32_e32 v61, 16, v117
	v_and_b32_e32 v117, 0xffff0000, v117
	v_mul_f32_e32 v56, v57, v57
	v_mul_f32_e32 v58, v59, v59
	v_pk_add_f32 v[2:3], v[26:27], v[2:3]
	v_lshlrev_b32_e32 v63, 16, v118
	v_and_b32_e32 v65, 0xffff0000, v118
	v_mul_f32_e32 v60, v61, v61
	v_mul_f32_e32 v116, v117, v117
	v_pk_add_f32 v[28:29], v[56:57], v[58:59]
	v_pk_add_f32 v[2:3], v[114:115], v[2:3]
	v_lshlrev_b32_e32 v67, 16, v119
	v_and_b32_e32 v119, 0xffff0000, v119
	v_mul_f32_e32 v62, v63, v63
	v_mul_f32_e32 v64, v65, v65
	v_pk_add_f32 v[116:117], v[60:61], v[116:117]
	v_pk_add_f32 v[2:3], v[2:3], v[28:29]
	v_mul_f32_e32 v66, v67, v67
	v_mul_f32_e32 v118, v119, v119
	s_waitcnt vmcnt(4)
; __device__ __forceinline__ float bflo(unsigned w) { return __uint_as_float(w << 16); }
; __device__ __forceinline__ float bfhi(unsigned w) { return __uint_as_float(w & 0xffff0000u); }
; __device__ __forceinline__ void phase_fix(KP kp, int l, unsigned char* shm) {
;     ...
; #pragma unroll 4
;         for (int e = 0; e < 16; ++e) {
;           const u32x4 rw = *(const u32x4*)(src + e * 8);
; #pragma unroll
;           for (int q = 0; q < 4; ++q) { const float a = bflo(rw[q]), b = bfhi(rw[q]); s += a + b; ss += a * a + b * b; }
;         }
;         s += __shfl_xor(s, 1); s += __shfl_xor(s, 2);
;         ss += __shfl_xor(ss, 1); ss += __shfl_xor(ss, 2);
;         const float mean = s * (1.f / 512.f);
;         const float var = fmaxf(ss * (1.f / 512.f) - mean * mean, 0.f);
;         const float rstd = rsqrtf(var + LN_EPS);
;         const float* gp = kp->sgu_g + l * 512 + qtr * 128;
;         const float* bp = kp->sgu_b + l * 512 + qtr * 128;
;         float* so = kp->out + O_SSV + ((size_t)l * MS + (rbase - MP) + row) * 512 + qtr * 128;
	v_lshlrev_b32_e32 v81, 16, v124
	v_and_b32_e32 v83, 0xffff0000, v124
	v_pk_add_f32 v[30:31], v[62:63], v[64:65]
	v_pk_add_f32 v[2:3], v[116:117], v[2:3]
	v_lshlrev_b32_e32 v85, 16, v125
	v_and_b32_e32 v125, 0xffff0000, v125
	v_pk_add_f32 v[118:119], v[66:67], v[118:119]
	v_mul_f32_e32 v80, v81, v81
	v_mul_f32_e32 v82, v83, v83
	v_pk_add_f32 v[2:3], v[30:31], v[2:3]
	v_lshlrev_b32_e32 v87, 16, v126
	v_and_b32_e32 v89, 0xffff0000, v126
	v_mul_f32_e32 v84, v85, v85
	v_mul_f32_e32 v124, v125, v125
	v_pk_add_f32 v[56:57], v[80:81], v[82:83]
	v_pk_add_f32 v[2:3], v[118:119], v[2:3]
	v_lshlrev_b32_e32 v91, 16, v127
	v_and_b32_e32 v127, 0xffff0000, v127
	v_mul_f32_e32 v86, v87, v87
	v_mul_f32_e32 v88, v89, v89
	v_pk_add_f32 v[124:125], v[84:85], v[124:125]
	v_pk_add_f32 v[2:3], v[2:3], v[56:57]
	v_mul_f32_e32 v90, v91, v91
	v_mul_f32_e32 v126, v127, v127
	v_pk_add_f32 v[58:59], v[86:87], v[88:89]
	v_pk_add_f32 v[2:3], v[124:125], v[2:3]
	v_pk_add_f32 v[126:127], v[90:91], v[126:127]
	v_pk_add_f32 v[2:3], v[58:59], v[2:3]
	s_nop 0
	v_pk_add_f32 v[2:3], v[126:127], v[2:3]
	s_waitcnt vmcnt(3)
	v_lshlrev_b32_e32 v15, 16, v128
	v_and_b32_e32 v27, 0xffff0000, v128
	v_lshlrev_b32_e32 v31, 16, v130
	v_and_b32_e32 v33, 0xffff0000, v130
	s_waitcnt vmcnt(1)
	v_lshlrev_b32_e32 v69, 16, v136
	v_and_b32_e32 v71, 0xffff0000, v136
	v_lshlrev_b32_e32 v73, 16, v137
	v_and_b32_e32 v137, 0xffff0000, v137
	v_mul_f32_e32 v14, v15, v15
	v_mul_f32_e32 v26, v27, v27
	v_mul_f32_e32 v30, v31, v31
	v_mul_f32_e32 v32, v33, v33
	v_mul_f32_e32 v68, v69, v69
	v_mul_f32_e32 v70, v71, v71
	v_lshlrev_b32_e32 v35, 16, v131
	v_and_b32_e32 v131, 0xffff0000, v131
	v_lshlrev_b32_e32 v75, 16, v138
	v_and_b32_e32 v77, 0xffff0000, v138
	v_mul_f32_e32 v72, v73, v73
	v_mul_f32_e32 v136, v137, v137
	v_pk_add_f32 v[14:15], v[14:15], v[26:27]
	v_pk_add_f32 v[26:27], v[30:31], v[32:33]
	v_pk_add_f32 v[32:33], v[68:69], v[70:71]
	v_lshlrev_b32_e32 v79, 16, v139
	v_and_b32_e32 v139, 0xffff0000, v139
	v_mul_f32_e32 v34, v35, v35
	v_mul_f32_e32 v130, v131, v131
	v_mul_f32_e32 v74, v75, v75
	v_mul_f32_e32 v76, v77, v77
	v_pk_add_f32 v[136:137], v[72:73], v[136:137]
	v_pk_add_f32 v[2:3], v[2:3], v[32:33]
	v_mul_f32_e32 v78, v79, v79
	v_mul_f32_e32 v138, v139, v139
	v_pk_add_f32 v[130:131], v[34:35], v[130:131]
	v_pk_add_f32 v[34:35], v[74:75], v[76:77]
	v_pk_add_f32 v[2:3], v[136:137], v[2:3]
	v_lshlrev_b32_e32 v29, 16, v129
	v_and_b32_e32 v129, 0xffff0000, v129
	v_pk_add_f32 v[138:139], v[78:79], v[138:139]
	v_pk_add_f32 v[2:3], v[34:35], v[2:3]
	v_mul_f32_e32 v28, v29, v29
	v_mul_f32_e32 v128, v129, v129
	v_pk_add_f32 v[2:3], v[138:139], v[2:3]
	v_pk_add_f32 v[128:129], v[28:29], v[128:129]
	v_pk_add_f32 v[2:3], v[2:3], v[14:15]
	v_lshlrev_b32_e32 v57, 16, v132
	v_and_b32_e32 v59, 0xffff0000, v132
	v_pk_add_f32 v[2:3], v[128:129], v[2:3]
	v_lshlrev_b32_e32 v61, 16, v133
	v_and_b32_e32 v133, 0xffff0000, v133
	v_mul_f32_e32 v56, v57, v57
	v_mul_f32_e32 v58, v59, v59
	v_pk_add_f32 v[2:3], v[26:27], v[2:3]
	v_lshlrev_b32_e32 v63, 16, v134
	v_and_b32_e32 v65, 0xffff0000, v134
	v_mul_f32_e32 v60, v61, v61
	v_mul_f32_e32 v132, v133, v133
	v_pk_add_f32 v[28:29], v[56:57], v[58:59]
	v_pk_add_f32 v[2:3], v[130:131], v[2:3]
	v_lshlrev_b32_e32 v67, 16, v135
	v_and_b32_e32 v135, 0xffff0000, v135
	v_mul_f32_e32 v62, v63, v63
	v_mul_f32_e32 v64, v65, v65
	v_pk_add_f32 v[132:133], v[60:61], v[132:133]
	v_pk_add_f32 v[2:3], v[2:3], v[28:29]
	v_mul_f32_e32 v66, v67, v67
	v_mul_f32_e32 v134, v135, v135
	s_waitcnt vmcnt(0)
	v_lshlrev_b32_e32 v81, 16, v140
	v_and_b32_e32 v83, 0xffff0000, v140
	v_pk_add_f32 v[30:31], v[62:63], v[64:65]
	v_pk_add_f32 v[2:3], v[132:133], v[2:3]
	v_lshlrev_b32_e32 v85, 16, v141
	v_and_b32_e32 v141, 0xffff0000, v141
	v_pk_add_f32 v[134:135], v[66:67], v[134:135]
	v_mul_f32_e32 v80, v81, v81
	v_mul_f32_e32 v82, v83, v83
	v_pk_add_f32 v[2:3], v[30:31], v[2:3]
	v_lshlrev_b32_e32 v87, 16, v142
	v_and_b32_e32 v89, 0xffff0000, v142
	v_mul_f32_e32 v84, v85, v85
	v_mul_f32_e32 v140, v141, v141
	v_pk_add_f32 v[56:57], v[80:81], v[82:83]
	v_pk_add_f32 v[2:3], v[134:135], v[2:3]
	v_lshlrev_b32_e32 v91, 16, v143
	v_and_b32_e32 v143, 0xffff0000, v143
	v_mul_f32_e32 v86, v87, v87
	v_mul_f32_e32 v88, v89, v89
	v_pk_add_f32 v[140:141], v[84:85], v[140:141]
	v_pk_add_f32 v[2:3], v[2:3], v[56:57]
	v_mul_f32_e32 v90, v91, v91
	v_mul_f32_e32 v142, v143, v143
	v_pk_add_f32 v[58:59], v[86:87], v[88:89]
	v_pk_add_f32 v[2:3], v[140:141], v[2:3]
	v_pk_add_f32 v[142:143], v[90:91], v[142:143]
	v_pk_add_f32 v[2:3], v[58:59], v[2:3]
	s_nop 0
	v_pk_add_f32 v[2:3], v[142:143], v[2:3]
	v_and_b32_e32 v5, 64, v252
	v_xor_b32_e32 v4, 1, v252
	v_add_u32_e32 v6, 64, v5
	v_cmp_lt_i32_e32 vcc, v4, v6
	v_xor_b32_e32 v7, 2, v252
	s_mov_b32 s10, 0x3b000000
	v_cndmask_b32_e32 v4, v252, v4, vcc
	v_lshlrev_b32_e32 v4, 2, v4
	ds_bpermute_b32 v5, v4, v3
	ds_bpermute_b32 v4, v4, v2
	v_cmp_lt_i32_e32 vcc, v7, v6
	s_load_dwordx4 s[36:39], s[12:13], 0x40
	v_mov_b32_e32 v55, v17
	v_cndmask_b32_e32 v6, v252, v7, vcc
	v_lshlrev_b32_e32 v6, 2, v6
	s_waitcnt lgkmcnt(0)
	v_pk_add_f32 v[2:3], v[2:3], v[4:5]
	ds_bpermute_b32 v5, v6, v3
	ds_bpermute_b32 v4, v6, v2
	v_lshl_add_u64 v[10:11], v[38:39], 0, v[0:1]
	v_mov_b32_e32 v16, v37
	s_waitcnt lgkmcnt(0)
	v_pk_add_f32 v[2:3], v[2:3], v[4:5]
	s_nop 0
	v_pk_mul_f32 v[8:9], v[2:3], s[10:11] op_sel_hi:[1,0]
	s_mov_b32 s10, 0x800000
	v_fma_f32 v2, -v9, v9, v8
	v_max_f32_e32 v2, 0, v2
	v_add_f32_e32 v2, 0x3727c5ac, v2
	v_mul_f32_e32 v3, 0x4b800000, v2
	v_cmp_gt_f32_e32 vcc, s10, v2
	s_load_dwordx2 s[10:11], s[12:13], 0xa8
	s_add_u32 s28, s36, s20
	v_cndmask_b32_e32 v2, v2, v3, vcc
	v_rsq_f32_e32 v2, v2
	s_addc_u32 s29, s37, s21
	v_lshl_add_u64 v[14:15], s[28:29], 0, v[54:55]
	s_add_u32 s28, s38, s20
	s_addc_u32 s29, s39, s21
	v_lshl_add_u64 v[18:19], s[28:29], 0, v[54:55]
	s_add_i32 s28, s31, 0xffff8000
	v_mul_f32_e32 v0, 0x45800000, v2
	s_ashr_i32 s29, s28, 31
	v_cndmask_b32_e32 v12, v2, v0, vcc
	v_lshl_add_u64 v[0:1], v[40:41], 0, s[28:29]
	v_lshlrev_b64 v[0:1], 11, v[0:1]
	s_waitcnt lgkmcnt(0)
	v_lshl_add_u64 v[2:3], s[10:11], 0, v[46:47]
	v_lshl_add_u64 v[0:1], v[2:3], 0, v[0:1]
	s_mov_b64 s[10:11], 0xd340020
	v_mov_b32_e32 v13, v12
	v_mov_b32_e32 v8, v9
	v_lshl_add_u64 v[20:21], v[0:1], 0, s[10:11]
	s_mov_b64 s[28:29], 0
	s_branch .LBB0_2815
